# phase 6 hand-written for the 512-block grid: 8 columns per thread, per-column constants hoisted, next item's loads in flight during compute
# speedup vs baseline: 1.0057x; 1.0015x over previous
.LBB0_545:
	s_or_b64 exec, exec, s[0:1]
	s_add_u32 s16, s94, 0x8c00000
	s_addc_u32 s17, s95, 0
	v_mov_b32_e32 v0, v199
	v_readlane_b32 s0, v242, 47
	s_barrier
	s_add_u32 s2, s94, 0xac00000
	s_addc_u32 s3, s95, 0
	v_add_u32_e32 v2, s0, v0
	s_mov_b32 s0, 0x400000
	v_cmp_gt_i32_e32 vcc, s0, v2
	s_and_saveexec_b64 s[6:7], vcc
	v_readlane_b32 s18, v242, 50
	v_readlane_b32 s19, v242, 51
	s_cbranch_execz .LBB0_548
	v_lshlrev_b32_e32 v0, 2, v0
	v_readlane_b32 s0, v242, 45
	s_lshl_b32 s10, s96, 10
	s_mov_b64 s[8:9], 0
	v_lshl_add_u32 v3, s0, 10, v0
	v_mov_b32_e32 v1, 0
	v_mov_b32_e32 v4, 0xffffe500
	s_movk_i32 s11, 0x1000
	s_movk_i32 s12, 0x2000
	s_mov_b32 s13, 0xf800000
	v_mov_b32_e32 v5, 0x260
	s_mov_b32 s14, 0x3fffff
	v_readlane_b32 s1, v242, 46
	s_cmp_lg_u32 s96, 0x200
	s_cbranch_scc1 .LBB0_547
	v_and_b32_e32 v152, 0x7f, v199
	v_lshlrev_b32_e32 v184, 4, v152
	v_add_u32_e32 v185, 0x1000, v184
	v_add_u32_e32 v186, 0x21c00000, v184
	v_add_u32_e32 v188, 0x6c00000, v184
	v_add_u32_e32 v189, 0x8c00000, v184
	v_add_u32_e32 v190, 0xac00000, v184
	v_add_u32_e32 v191, 0x15000000, v184
	v_add_u32_e32 v192, 0x17000000, v184
	v_lshlrev_b32_e32 v187, 5, v152
	s_add_u32 s0, s82, 0x1000
	s_addc_u32 s1, s83, 0
	s_add_u32 s2, s82, 0x2000
	s_addc_u32 s3, s83, 0
	global_load_dwordx4 v[48:51], v187, s[82:83]
	global_load_dwordx4 v[52:55], v187, s[82:83] offset:16
	global_load_dwordx4 v[56:59], v187, s[0:1]
	global_load_dwordx4 v[60:63], v187, s[0:1] offset:16
	global_load_dwordx4 v[64:67], v187, s[2:3]
	global_load_dwordx4 v[68:71], v187, s[2:3] offset:16
	global_load_dwordx4 v[72:75], v187, s[62:63]
	global_load_dwordx4 v[76:79], v187, s[62:63] offset:16
	global_load_dwordx4 v[80:83], v187, s[64:65]
	global_load_dwordx4 v[84:87], v187, s[64:65] offset:16
	v_lshrrev_b32_e32 v152, 7, v199
	s_nop 0
	v_readfirstlane_b32 s34, v152
	v_readlane_b32 s14, v242, 45
	s_lshl_b32 s14, s14, 1
	s_add_u32 s14, s14, s34
	s_mov_b32 s36, s14
	s_mul_i32 s34, s14, 0x1b00
	s_mul_hi_u32 s35, s14, 0x1b00
	s_add_u32 s8, s94, s34
	s_addc_u32 s9, s95, s35
	s_lshl_b32 s34, s14, 11
	s_add_u32 s12, s94, s34
	s_addc_u32 s13, s95, 0
	s_mov_b64 s[32:33], s[12:13]
	s_waitcnt vmcnt(0)
	v_sub_f32_e32 v144, 1.0, v80
	v_sub_f32_e32 v145, 1.0, v81
	v_sub_f32_e32 v146, 1.0, v82
	v_sub_f32_e32 v147, 1.0, v83
	v_sub_f32_e32 v148, 1.0, v84
	v_sub_f32_e32 v149, 1.0, v85
	v_sub_f32_e32 v150, 1.0, v86
	v_sub_f32_e32 v151, 1.0, v87
	s_and_b32 s34, s14, 0xfff
	s_cmp_eq_u32 s34, 0
	s_cselect_b32 s34, 0, 0x1b00
	s_sub_u32 s10, s8, s34
	s_subb_u32 s11, s9, 0
	global_load_dwordx4 v[88:91], v184, s[8:9]
	global_load_dwordx4 v[92:95], v184, s[8:9] offset:2048
	global_load_dwordx4 v[96:99], v185, s[8:9]
	global_load_dwordx4 v[100:103], v184, s[10:11]
	global_load_dwordx4 v[104:107], v184, s[10:11] offset:2048
	global_load_dwordx4 v[108:111], v185, s[10:11]
	global_load_dwordx4 v[112:115], v186, s[12:13]
	s_add_u32 s8, s8, 0x6c0000
	s_addc_u32 s9, s9, 0
	s_add_u32 s12, s12, 0x200000
	s_addc_u32 s13, s13, 0
	s_add_u32 s14, s14, 0x400
	s_mov_b32 s15, 8
.Lp6_loop:
	s_and_b32 s34, s14, 0xfff
	s_cmp_eq_u32 s34, 0
	s_cselect_b32 s34, 0, 0x1b00
	s_sub_u32 s10, s8, s34
	s_subb_u32 s11, s9, 0
	global_load_dwordx4 v[116:119], v184, s[8:9]
	global_load_dwordx4 v[120:123], v184, s[8:9] offset:2048
	global_load_dwordx4 v[124:127], v185, s[8:9]
	global_load_dwordx4 v[128:131], v184, s[10:11]
	global_load_dwordx4 v[132:135], v184, s[10:11] offset:2048
	global_load_dwordx4 v[136:139], v185, s[10:11]
	global_load_dwordx4 v[140:143], v186, s[12:13]
	s_add_u32 s8, s8, 0x6c0000
	s_addc_u32 s9, s9, 0
	s_add_u32 s12, s12, 0x200000
	s_addc_u32 s13, s13, 0
	s_add_u32 s14, s14, 0x400
	s_waitcnt vmcnt(7)
	s_and_b32 s34, s36, 0xfff
	v_lshlrev_b32_e32 v0, 16, v88
	v_and_b32_e32 v1, 0xffff0000, v88
	v_lshlrev_b32_e32 v2, 16, v89
	v_and_b32_e32 v3, 0xffff0000, v89
	v_lshlrev_b32_e32 v4, 16, v90
	v_and_b32_e32 v5, 0xffff0000, v90
	v_lshlrev_b32_e32 v6, 16, v91
	v_and_b32_e32 v7, 0xffff0000, v91
	v_lshlrev_b32_e32 v24, 16, v100
	v_and_b32_e32 v25, 0xffff0000, v100
	v_lshlrev_b32_e32 v26, 16, v101
	v_and_b32_e32 v27, 0xffff0000, v101
	v_lshlrev_b32_e32 v28, 16, v102
	v_and_b32_e32 v29, 0xffff0000, v102
	v_lshlrev_b32_e32 v30, 16, v103
	v_and_b32_e32 v31, 0xffff0000, v103
	s_cmp_lg_u32 s34, 0
	s_cbranch_scc1 .Lp6_hpa_0
	v_mov_b32_e32 v24, 0
	v_mov_b32_e32 v25, 0
	v_mov_b32_e32 v26, 0
	v_mov_b32_e32 v27, 0
	v_mov_b32_e32 v28, 0
	v_mov_b32_e32 v29, 0
	v_mov_b32_e32 v30, 0
	v_mov_b32_e32 v31, 0
.Lp6_hpa_0:
	v_pk_add_f32 v[24:25], v[24:25], v[0:1] neg_lo:[0,1] neg_hi:[0,1]
	v_pk_fma_f32 v[0:1], v[48:49], v[24:25], v[0:1]
	v_pk_add_f32 v[26:27], v[26:27], v[2:3] neg_lo:[0,1] neg_hi:[0,1]
	v_pk_fma_f32 v[2:3], v[50:51], v[26:27], v[2:3]
	v_pk_add_f32 v[28:29], v[28:29], v[4:5] neg_lo:[0,1] neg_hi:[0,1]
	v_pk_fma_f32 v[4:5], v[52:53], v[28:29], v[4:5]
	v_pk_add_f32 v[30:31], v[30:31], v[6:7] neg_lo:[0,1] neg_hi:[0,1]
	v_pk_fma_f32 v[6:7], v[54:55], v[30:31], v[6:7]
	v_lshlrev_b32_e32 v8, 16, v92
	v_and_b32_e32 v9, 0xffff0000, v92
	v_lshlrev_b32_e32 v10, 16, v93
	v_and_b32_e32 v11, 0xffff0000, v93
	v_lshlrev_b32_e32 v12, 16, v94
	v_and_b32_e32 v13, 0xffff0000, v94
	v_lshlrev_b32_e32 v14, 16, v95
	v_and_b32_e32 v15, 0xffff0000, v95
	v_lshlrev_b32_e32 v24, 16, v104
	v_and_b32_e32 v25, 0xffff0000, v104
	v_lshlrev_b32_e32 v26, 16, v105
	v_and_b32_e32 v27, 0xffff0000, v105
	v_lshlrev_b32_e32 v28, 16, v106
	v_and_b32_e32 v29, 0xffff0000, v106
	v_lshlrev_b32_e32 v30, 16, v107
	v_and_b32_e32 v31, 0xffff0000, v107
	s_cmp_lg_u32 s34, 0
	s_cbranch_scc1 .Lp6_hpa_1
	v_mov_b32_e32 v24, 0
	v_mov_b32_e32 v25, 0
	v_mov_b32_e32 v26, 0
	v_mov_b32_e32 v27, 0
	v_mov_b32_e32 v28, 0
	v_mov_b32_e32 v29, 0
	v_mov_b32_e32 v30, 0
	v_mov_b32_e32 v31, 0
.Lp6_hpa_1:
	v_pk_add_f32 v[24:25], v[24:25], v[8:9] neg_lo:[0,1] neg_hi:[0,1]
	v_pk_fma_f32 v[8:9], v[56:57], v[24:25], v[8:9]
	v_pk_add_f32 v[26:27], v[26:27], v[10:11] neg_lo:[0,1] neg_hi:[0,1]
	v_pk_fma_f32 v[10:11], v[58:59], v[26:27], v[10:11]
	v_pk_add_f32 v[28:29], v[28:29], v[12:13] neg_lo:[0,1] neg_hi:[0,1]
	v_pk_fma_f32 v[12:13], v[60:61], v[28:29], v[12:13]
	v_pk_add_f32 v[30:31], v[30:31], v[14:15] neg_lo:[0,1] neg_hi:[0,1]
	v_pk_fma_f32 v[14:15], v[62:63], v[30:31], v[14:15]
	v_lshlrev_b32_e32 v16, 16, v96
	v_and_b32_e32 v17, 0xffff0000, v96
	v_lshlrev_b32_e32 v18, 16, v97
	v_and_b32_e32 v19, 0xffff0000, v97
	v_lshlrev_b32_e32 v20, 16, v98
	v_and_b32_e32 v21, 0xffff0000, v98
	v_lshlrev_b32_e32 v22, 16, v99
	v_and_b32_e32 v23, 0xffff0000, v99
	v_lshlrev_b32_e32 v24, 16, v108
	v_and_b32_e32 v25, 0xffff0000, v108
	v_lshlrev_b32_e32 v26, 16, v109
	v_and_b32_e32 v27, 0xffff0000, v109
	v_lshlrev_b32_e32 v28, 16, v110
	v_and_b32_e32 v29, 0xffff0000, v110
	v_lshlrev_b32_e32 v30, 16, v111
	v_and_b32_e32 v31, 0xffff0000, v111
	s_cmp_lg_u32 s34, 0
	s_cbranch_scc1 .Lp6_hpa_2
	v_mov_b32_e32 v24, 0
	v_mov_b32_e32 v25, 0
	v_mov_b32_e32 v26, 0
	v_mov_b32_e32 v27, 0
	v_mov_b32_e32 v28, 0
	v_mov_b32_e32 v29, 0
	v_mov_b32_e32 v30, 0
	v_mov_b32_e32 v31, 0
.Lp6_hpa_2:
	v_pk_add_f32 v[24:25], v[24:25], v[16:17] neg_lo:[0,1] neg_hi:[0,1]
	v_pk_fma_f32 v[16:17], v[64:65], v[24:25], v[16:17]
	v_pk_add_f32 v[26:27], v[26:27], v[18:19] neg_lo:[0,1] neg_hi:[0,1]
	v_pk_fma_f32 v[18:19], v[66:67], v[26:27], v[18:19]
	v_pk_add_f32 v[28:29], v[28:29], v[20:21] neg_lo:[0,1] neg_hi:[0,1]
	v_pk_fma_f32 v[20:21], v[68:69], v[28:29], v[20:21]
	v_pk_add_f32 v[30:31], v[30:31], v[22:23] neg_lo:[0,1] neg_hi:[0,1]
	v_pk_fma_f32 v[22:23], v[70:71], v[30:31], v[22:23]
	v_lshlrev_b32_e32 v32, 16, v112
	v_and_b32_e32 v33, 0xffff0000, v112
	v_lshlrev_b32_e32 v34, 16, v113
	v_and_b32_e32 v35, 0xffff0000, v113
	v_lshlrev_b32_e32 v36, 16, v114
	v_and_b32_e32 v37, 0xffff0000, v114
	v_lshlrev_b32_e32 v38, 16, v115
	v_and_b32_e32 v39, 0xffff0000, v115
	v_pk_mul_f32 v[40:41], v[8:9], v[72:73]
	v_pk_mul_f32 v[42:43], v[10:11], v[74:75]
	v_pk_mul_f32 v[44:45], v[12:13], v[76:77]
	v_pk_mul_f32 v[46:47], v[14:15], v[78:79]
	v_pk_mul_f32 v[160:161], v[40:41], v[40:41]
	v_pk_fma_f32 v[160:161], v[42:43], v[42:43], v[160:161]
	v_pk_fma_f32 v[160:161], v[44:45], v[44:45], v[160:161]
	v_pk_fma_f32 v[160:161], v[46:47], v[46:47], v[160:161]
	v_add_f32_e32 v160, v160, v161
	v_pk_fma_f32 v[152:153], v[32:33], v[80:81], v[144:145]
	v_pk_fma_f32 v[154:155], v[34:35], v[82:83], v[146:147]
	v_add_f32_dpp v160, v160, v160 quad_perm:[1,0,3,2] row_mask:0xf bank_mask:0xf bound_ctrl:1
	v_pk_fma_f32 v[156:157], v[36:37], v[84:85], v[148:149]
	v_pk_fma_f32 v[158:159], v[38:39], v[86:87], v[150:151]
	v_add_f32_dpp v160, v160, v160 quad_perm:[2,3,0,1] row_mask:0xf bank_mask:0xf bound_ctrl:1
	v_pk_mul_f32 v[152:153], v[8:9], v[152:153]
	v_pk_mul_f32 v[154:155], v[10:11], v[154:155]
	v_add_f32_dpp v160, v160, v160 row_half_mirror row_mask:0xf bank_mask:0xf bound_ctrl:1
	v_pk_mul_f32 v[156:157], v[12:13], v[156:157]
	v_pk_mul_f32 v[158:159], v[14:15], v[158:159]
	v_sqrt_f32_e32 v162, v160
	s_nop 0
	v_max_f32_e32 v162, 0x2b8cbccc, v162
	v_rcp_f32_e32 v162, v162
	v_cvt_pk_bf16_f32 v164, v0, v1
	v_cvt_pk_bf16_f32 v165, v2, v3
	v_cvt_pk_bf16_f32 v166, v4, v5
	v_cvt_pk_bf16_f32 v167, v6, v7
	v_pk_mul_f32 v[40:41], v[40:41], v[162:163] op_sel_hi:[1,0]
	v_pk_mul_f32 v[42:43], v[42:43], v[162:163] op_sel_hi:[1,0]
	v_pk_mul_f32 v[44:45], v[44:45], v[162:163] op_sel_hi:[1,0]
	v_pk_mul_f32 v[46:47], v[46:47], v[162:163] op_sel_hi:[1,0]
	v_pk_mul_f32 v[32:33], v[32:33], v[40:41]
	v_pk_mul_f32 v[34:35], v[34:35], v[42:43]
	v_pk_mul_f32 v[36:37], v[36:37], v[44:45]
	v_pk_mul_f32 v[38:39], v[38:39], v[46:47]
	v_cvt_pk_bf16_f32 v168, v152, v153
	v_cvt_pk_bf16_f32 v172, v40, v41
	v_cvt_pk_bf16_f32 v176, v32, v33
	v_cvt_pk_bf16_f32 v180, v16, v17
	v_cvt_pk_bf16_f32 v169, v154, v155
	v_cvt_pk_bf16_f32 v173, v42, v43
	v_cvt_pk_bf16_f32 v177, v34, v35
	v_cvt_pk_bf16_f32 v181, v18, v19
	v_cvt_pk_bf16_f32 v170, v156, v157
	v_cvt_pk_bf16_f32 v174, v44, v45
	v_cvt_pk_bf16_f32 v178, v36, v37
	v_cvt_pk_bf16_f32 v182, v20, v21
	v_cvt_pk_bf16_f32 v171, v158, v159
	v_cvt_pk_bf16_f32 v175, v46, v47
	v_cvt_pk_bf16_f32 v179, v38, v39
	v_cvt_pk_bf16_f32 v183, v22, v23
	global_store_dwordx4 v188, v[164:167], s[32:33]
	global_store_dwordx4 v189, v[168:171], s[32:33]
	global_store_dwordx4 v190, v[172:175], s[32:33]
	global_store_dwordx4 v191, v[176:179], s[32:33]
	global_store_dwordx4 v192, v[180:183], s[32:33]
	s_add_u32 s32, s32, 0x200000
	s_addc_u32 s33, s33, 0
	s_add_u32 s36, s36, 0x400
	s_and_b32 s34, s14, 0xfff
	s_cmp_eq_u32 s34, 0
	s_cselect_b32 s34, 0, 0x1b00
	s_sub_u32 s10, s8, s34
	s_subb_u32 s11, s9, 0
	global_load_dwordx4 v[88:91], v184, s[8:9]
	global_load_dwordx4 v[92:95], v184, s[8:9] offset:2048
	global_load_dwordx4 v[96:99], v185, s[8:9]
	global_load_dwordx4 v[100:103], v184, s[10:11]
	global_load_dwordx4 v[104:107], v184, s[10:11] offset:2048
	global_load_dwordx4 v[108:111], v185, s[10:11]
	global_load_dwordx4 v[112:115], v186, s[12:13]
	s_add_u32 s8, s8, 0x6c0000
	s_addc_u32 s9, s9, 0
	s_add_u32 s12, s12, 0x200000
	s_addc_u32 s13, s13, 0
	s_add_u32 s14, s14, 0x400
	s_waitcnt vmcnt(12)
	s_and_b32 s34, s36, 0xfff
	v_lshlrev_b32_e32 v0, 16, v116
	v_and_b32_e32 v1, 0xffff0000, v116
	v_lshlrev_b32_e32 v2, 16, v117
	v_and_b32_e32 v3, 0xffff0000, v117
	v_lshlrev_b32_e32 v4, 16, v118
	v_and_b32_e32 v5, 0xffff0000, v118
	v_lshlrev_b32_e32 v6, 16, v119
	v_and_b32_e32 v7, 0xffff0000, v119
	v_lshlrev_b32_e32 v24, 16, v128
	v_and_b32_e32 v25, 0xffff0000, v128
	v_lshlrev_b32_e32 v26, 16, v129
	v_and_b32_e32 v27, 0xffff0000, v129
	v_lshlrev_b32_e32 v28, 16, v130
	v_and_b32_e32 v29, 0xffff0000, v130
	v_lshlrev_b32_e32 v30, 16, v131
	v_and_b32_e32 v31, 0xffff0000, v131
	s_cmp_lg_u32 s34, 0
	s_cbranch_scc1 .Lp6_hpb_0
	v_mov_b32_e32 v24, 0
	v_mov_b32_e32 v25, 0
	v_mov_b32_e32 v26, 0
	v_mov_b32_e32 v27, 0
	v_mov_b32_e32 v28, 0
	v_mov_b32_e32 v29, 0
	v_mov_b32_e32 v30, 0
	v_mov_b32_e32 v31, 0
.Lp6_hpb_0:
	v_pk_add_f32 v[24:25], v[24:25], v[0:1] neg_lo:[0,1] neg_hi:[0,1]
	v_pk_fma_f32 v[0:1], v[48:49], v[24:25], v[0:1]
	v_pk_add_f32 v[26:27], v[26:27], v[2:3] neg_lo:[0,1] neg_hi:[0,1]
	v_pk_fma_f32 v[2:3], v[50:51], v[26:27], v[2:3]
	v_pk_add_f32 v[28:29], v[28:29], v[4:5] neg_lo:[0,1] neg_hi:[0,1]
	v_pk_fma_f32 v[4:5], v[52:53], v[28:29], v[4:5]
	v_pk_add_f32 v[30:31], v[30:31], v[6:7] neg_lo:[0,1] neg_hi:[0,1]
	v_pk_fma_f32 v[6:7], v[54:55], v[30:31], v[6:7]
	v_lshlrev_b32_e32 v8, 16, v120
	v_and_b32_e32 v9, 0xffff0000, v120
	v_lshlrev_b32_e32 v10, 16, v121
	v_and_b32_e32 v11, 0xffff0000, v121
	v_lshlrev_b32_e32 v12, 16, v122
	v_and_b32_e32 v13, 0xffff0000, v122
	v_lshlrev_b32_e32 v14, 16, v123
	v_and_b32_e32 v15, 0xffff0000, v123
	v_lshlrev_b32_e32 v24, 16, v132
	v_and_b32_e32 v25, 0xffff0000, v132
	v_lshlrev_b32_e32 v26, 16, v133
	v_and_b32_e32 v27, 0xffff0000, v133
	v_lshlrev_b32_e32 v28, 16, v134
	v_and_b32_e32 v29, 0xffff0000, v134
	v_lshlrev_b32_e32 v30, 16, v135
	v_and_b32_e32 v31, 0xffff0000, v135
	s_cmp_lg_u32 s34, 0
	s_cbranch_scc1 .Lp6_hpb_1
	v_mov_b32_e32 v24, 0
	v_mov_b32_e32 v25, 0
	v_mov_b32_e32 v26, 0
	v_mov_b32_e32 v27, 0
	v_mov_b32_e32 v28, 0
	v_mov_b32_e32 v29, 0
	v_mov_b32_e32 v30, 0
	v_mov_b32_e32 v31, 0
.Lp6_hpb_1:
	v_pk_add_f32 v[24:25], v[24:25], v[8:9] neg_lo:[0,1] neg_hi:[0,1]
	v_pk_fma_f32 v[8:9], v[56:57], v[24:25], v[8:9]
	v_pk_add_f32 v[26:27], v[26:27], v[10:11] neg_lo:[0,1] neg_hi:[0,1]
	v_pk_fma_f32 v[10:11], v[58:59], v[26:27], v[10:11]
	v_pk_add_f32 v[28:29], v[28:29], v[12:13] neg_lo:[0,1] neg_hi:[0,1]
	v_pk_fma_f32 v[12:13], v[60:61], v[28:29], v[12:13]
	v_pk_add_f32 v[30:31], v[30:31], v[14:15] neg_lo:[0,1] neg_hi:[0,1]
	v_pk_fma_f32 v[14:15], v[62:63], v[30:31], v[14:15]
	v_lshlrev_b32_e32 v16, 16, v124
	v_and_b32_e32 v17, 0xffff0000, v124
	v_lshlrev_b32_e32 v18, 16, v125
	v_and_b32_e32 v19, 0xffff0000, v125
	v_lshlrev_b32_e32 v20, 16, v126
	v_and_b32_e32 v21, 0xffff0000, v126
	v_lshlrev_b32_e32 v22, 16, v127
	v_and_b32_e32 v23, 0xffff0000, v127
	v_lshlrev_b32_e32 v24, 16, v136
	v_and_b32_e32 v25, 0xffff0000, v136
	v_lshlrev_b32_e32 v26, 16, v137
	v_and_b32_e32 v27, 0xffff0000, v137
	v_lshlrev_b32_e32 v28, 16, v138
	v_and_b32_e32 v29, 0xffff0000, v138
	v_lshlrev_b32_e32 v30, 16, v139
	v_and_b32_e32 v31, 0xffff0000, v139
	s_cmp_lg_u32 s34, 0
	s_cbranch_scc1 .Lp6_hpb_2
	v_mov_b32_e32 v24, 0
	v_mov_b32_e32 v25, 0
	v_mov_b32_e32 v26, 0
	v_mov_b32_e32 v27, 0
	v_mov_b32_e32 v28, 0
	v_mov_b32_e32 v29, 0
	v_mov_b32_e32 v30, 0
	v_mov_b32_e32 v31, 0
.Lp6_hpb_2:
	v_pk_add_f32 v[24:25], v[24:25], v[16:17] neg_lo:[0,1] neg_hi:[0,1]
	v_pk_fma_f32 v[16:17], v[64:65], v[24:25], v[16:17]
	v_pk_add_f32 v[26:27], v[26:27], v[18:19] neg_lo:[0,1] neg_hi:[0,1]
	v_pk_fma_f32 v[18:19], v[66:67], v[26:27], v[18:19]
	v_pk_add_f32 v[28:29], v[28:29], v[20:21] neg_lo:[0,1] neg_hi:[0,1]
	v_pk_fma_f32 v[20:21], v[68:69], v[28:29], v[20:21]
	v_pk_add_f32 v[30:31], v[30:31], v[22:23] neg_lo:[0,1] neg_hi:[0,1]
	v_pk_fma_f32 v[22:23], v[70:71], v[30:31], v[22:23]
	v_lshlrev_b32_e32 v32, 16, v140
	v_and_b32_e32 v33, 0xffff0000, v140
	v_lshlrev_b32_e32 v34, 16, v141
	v_and_b32_e32 v35, 0xffff0000, v141
	v_lshlrev_b32_e32 v36, 16, v142
	v_and_b32_e32 v37, 0xffff0000, v142
	v_lshlrev_b32_e32 v38, 16, v143
	v_and_b32_e32 v39, 0xffff0000, v143
	v_pk_mul_f32 v[40:41], v[8:9], v[72:73]
	v_pk_mul_f32 v[42:43], v[10:11], v[74:75]
	v_pk_mul_f32 v[44:45], v[12:13], v[76:77]
	v_pk_mul_f32 v[46:47], v[14:15], v[78:79]
	v_pk_mul_f32 v[160:161], v[40:41], v[40:41]
	v_pk_fma_f32 v[160:161], v[42:43], v[42:43], v[160:161]
	v_pk_fma_f32 v[160:161], v[44:45], v[44:45], v[160:161]
	v_pk_fma_f32 v[160:161], v[46:47], v[46:47], v[160:161]
	v_add_f32_e32 v160, v160, v161
	v_pk_fma_f32 v[152:153], v[32:33], v[80:81], v[144:145]
	v_pk_fma_f32 v[154:155], v[34:35], v[82:83], v[146:147]
	v_add_f32_dpp v160, v160, v160 quad_perm:[1,0,3,2] row_mask:0xf bank_mask:0xf bound_ctrl:1
	v_pk_fma_f32 v[156:157], v[36:37], v[84:85], v[148:149]
	v_pk_fma_f32 v[158:159], v[38:39], v[86:87], v[150:151]
	v_add_f32_dpp v160, v160, v160 quad_perm:[2,3,0,1] row_mask:0xf bank_mask:0xf bound_ctrl:1
	v_pk_mul_f32 v[152:153], v[8:9], v[152:153]
	v_pk_mul_f32 v[154:155], v[10:11], v[154:155]
	v_add_f32_dpp v160, v160, v160 row_half_mirror row_mask:0xf bank_mask:0xf bound_ctrl:1
	v_pk_mul_f32 v[156:157], v[12:13], v[156:157]
	v_pk_mul_f32 v[158:159], v[14:15], v[158:159]
	v_sqrt_f32_e32 v162, v160
	s_nop 0
	v_max_f32_e32 v162, 0x2b8cbccc, v162
	v_rcp_f32_e32 v162, v162
	v_cvt_pk_bf16_f32 v164, v0, v1
	v_cvt_pk_bf16_f32 v165, v2, v3
	v_cvt_pk_bf16_f32 v166, v4, v5
	v_cvt_pk_bf16_f32 v167, v6, v7
	v_pk_mul_f32 v[40:41], v[40:41], v[162:163] op_sel_hi:[1,0]
	v_pk_mul_f32 v[42:43], v[42:43], v[162:163] op_sel_hi:[1,0]
	v_pk_mul_f32 v[44:45], v[44:45], v[162:163] op_sel_hi:[1,0]
	v_pk_mul_f32 v[46:47], v[46:47], v[162:163] op_sel_hi:[1,0]
	v_pk_mul_f32 v[32:33], v[32:33], v[40:41]
	v_pk_mul_f32 v[34:35], v[34:35], v[42:43]
	v_pk_mul_f32 v[36:37], v[36:37], v[44:45]
	v_pk_mul_f32 v[38:39], v[38:39], v[46:47]
	v_cvt_pk_bf16_f32 v168, v152, v153
	v_cvt_pk_bf16_f32 v172, v40, v41
	v_cvt_pk_bf16_f32 v176, v32, v33
	v_cvt_pk_bf16_f32 v180, v16, v17
	v_cvt_pk_bf16_f32 v169, v154, v155
	v_cvt_pk_bf16_f32 v173, v42, v43
	v_cvt_pk_bf16_f32 v177, v34, v35
	v_cvt_pk_bf16_f32 v181, v18, v19
	v_cvt_pk_bf16_f32 v170, v156, v157
	v_cvt_pk_bf16_f32 v174, v44, v45
	v_cvt_pk_bf16_f32 v178, v36, v37
	v_cvt_pk_bf16_f32 v182, v20, v21
	v_cvt_pk_bf16_f32 v171, v158, v159
	v_cvt_pk_bf16_f32 v175, v46, v47
	v_cvt_pk_bf16_f32 v179, v38, v39
	v_cvt_pk_bf16_f32 v183, v22, v23
	global_store_dwordx4 v188, v[164:167], s[32:33]
	global_store_dwordx4 v189, v[168:171], s[32:33]
	global_store_dwordx4 v190, v[172:175], s[32:33]
	global_store_dwordx4 v191, v[176:179], s[32:33]
	global_store_dwordx4 v192, v[180:183], s[32:33]
	s_add_u32 s32, s32, 0x200000
	s_addc_u32 s33, s33, 0
	s_add_u32 s36, s36, 0x400
	s_sub_u32 s15, s15, 1
	s_cmp_lg_u32 s15, 0
	s_cbranch_scc1 .Lp6_loop
	s_waitcnt vmcnt(0)
	s_branch .LBB0_548
